# queue loops: prefetched next index published before the unit's final barrier; loop top without barriers (on top of combined stack)
# baseline (speedup 1.0000x reference)
; __global__ void __launch_bounds__(NWAVES * 64, 2) hybrid_fwd(Args args) {
;     ...
;                 for (;;) {
;                     if (threadIdx.x == 0) *slot = __hip_atomic_fetch_add(qc, 1u, __ATOMIC_RELAXED, __HIP_MEMORY_SCOPE_AGENT);
;                     __syncthreads();
;                     const int L = __builtin_amdgcn_readfirstlane((int)*slot);
;                     __syncthreads();
;                     if (L >= CHB * 16 * 32 + CHB * 16) break;
.LBB0_406:
	s_cmp_eq_u32 s99, 0
	s_cbranch_scc1 .Lq2_slow
	v_mov_b32_e32 v0, s86
	ds_read_b32 v0, v0
	s_mov_b64 s[4:5], -1
	s_waitcnt lgkmcnt(0)
	s_branch .Lq2_join

; __global__ void __launch_bounds__(NWAVES * 64, 2) hybrid_fwd(Args args) {
;     ...
;                 for (;;) {
;                     if (threadIdx.x == 0) *slot = __hip_atomic_fetch_add(qc, 1u, __ATOMIC_RELAXED, __HIP_MEMORY_SCOPE_AGENT);
;                     __syncthreads();
;                     const int L = __builtin_amdgcn_readfirstlane((int)*slot);
;                     __syncthreads();
;                     if (L >= CHB * 16 * 32 + CHB * 16) break;
;                     if (L >= CHB * 16) { const int L1 = L - CHB * 16; lru_unit<1>(lp, lds, chunk, L1 >> 9, (L1 >> 5) & 15, L1 & 31); }
.Lq2_join:
	v_readfirstlane_b32 s46, v0
	s_cmpk_gt_i32 s46, 0x41f
	s_cbranch_scc1 .LBB0_405
	s_mov_b32 s99, 0
	s_cmpk_lt_i32 s46, 0x2e0
	s_cbranch_scc0 .Lq2_nopf
	s_mov_b32 s99, 1
	s_and_saveexec_b64 s[42:43], s[10:11]
	s_cbranch_execz .Lq2_nopx
	v_mov_b32_e32 v252, v230
	global_atomic_add v252, v1, v252, s[38:39] sc0

; #define GAS __attribute__((address_space(1)))
; template <int PASS>
; __device__ __forceinline__ void lru_unit(const LruPtrs& args, LAS unsigned char* lds, int chunk, int bl, int g, int ck) {
;     ...
;         { const float* src = (w < 4) ? args.conv_w + w * D : (w == 4) ? args.conv_b : (w == 5) ? args.b_lru_r : (w == 6) ? args.b_lru_i : (const float*)(ws + WS_COEF);
;           PRM[w * 64 + lane] = ((const GAS float*)src)[g * 64 + lane]; }
; __device__ __forceinline__ void cumsum_unit(float* CBh, LAS unsigned char* lds) {
;     ...
;     for (int j = 0; j < 4; ++j) { f32x4 o;
; #pragma unroll
;         for (int e = 0; e < 4; ++e) o[e] = -(off + v[j][e]) * LOG2E;
;         *(f32x4*)(CBh + tid * 16 + 4 * j) = o; }
;     __syncthreads();
.LBB0_418:
	s_or_b64 exec, exec, s[4:5]
	v_pk_add_f32 v[20:21], v[18:19], v[0:1] op_sel_hi:[1,0]
	v_pk_add_f32 v[16:17], v[16:17], v[0:1] op_sel_hi:[1,0]
	v_pk_add_f32 v[12:13], v[12:13], v[0:1] op_sel_hi:[1,0]
	v_pk_mul_f32 v[18:19], v[16:17], s[24:25] op_sel_hi:[1,0]
	v_pk_mul_f32 v[16:17], v[20:21], s[24:25] op_sel_hi:[1,0]
	global_store_dwordx4 v[2:3], v[16:19], off
	v_pk_add_f32 v[8:9], v[8:9], v[0:1] op_sel_hi:[1,0]
	v_pk_add_f32 v[4:5], v[4:5], v[0:1] op_sel_hi:[1,0]
	v_pk_add_f32 v[16:17], v[14:15], v[0:1] op_sel_hi:[1,0]
	v_pk_mul_f32 v[14:15], v[12:13], s[24:25] op_sel_hi:[1,0]
	v_pk_mul_f32 v[12:13], v[16:17], s[24:25] op_sel_hi:[1,0]
	global_store_dwordx4 v[2:3], v[12:15], off offset:16
	s_mov_b64 s[4:5], 0
	s_nop 0
	v_pk_add_f32 v[12:13], v[10:11], v[0:1] op_sel_hi:[1,0]
	v_pk_mul_f32 v[10:11], v[8:9], s[24:25] op_sel_hi:[1,0]
	v_pk_mul_f32 v[8:9], v[12:13], s[24:25] op_sel_hi:[1,0]
	global_store_dwordx4 v[2:3], v[8:11], off offset:32
	s_nop 1
	v_pk_add_f32 v[8:9], v[6:7], v[0:1] op_sel_hi:[1,0]
	v_pk_mul_f32 v[6:7], v[4:5], s[24:25] op_sel_hi:[1,0]
	v_pk_mul_f32 v[4:5], v[8:9], s[24:25] op_sel_hi:[1,0]
	global_store_dwordx4 v[2:3], v[4:7], off offset:48
	s_cmp_eq_u32 s99, 0
	s_cbranch_scc1 .Lqwd
	s_and_saveexec_b64 s[100:101], s[10:11]
	v_mov_b32_e32 v253, s86
	ds_write_b32 v253, v252
	s_or_b64 exec, exec, s[100:101]
	s_waitcnt lgkmcnt(0)
.Lqwd:
	s_barrier
.LBB0_419:
	s_and_b64 vcc, exec, s[4:5]
	s_cbranch_vccz .LBB0_404
	v_mov_b32_e32 v24, v236
	s_mov_b64 s[42:43], s[40:41]
	v_readfirstlane_b32 s18, v24
	s_ashr_i32 s48, s18, 6
	s_cmp_gt_i32 s48, 3
	s_mov_b64 s[44:45], -1
	s_cbranch_scc0 .LBB0_431
	s_cmp_lt_i32 s48, 5
	s_mov_b64 s[4:5], s[14:15]
	s_cbranch_scc1 .LBB0_430
	s_cmp_lt_i32 s48, 6
	s_cbranch_scc1 .LBB0_428
	s_cmp_lg_u32 s48, 6
	s_cbranch_scc0 .LBB0_425
	s_add_u32 s4, s42, 0x2580000
	s_addc_u32 s5, s43, 0
	s_mov_b64 s[44:45], 0

; #define PG8_LAS __attribute__((address_space(3)))
; #define GAS __attribute__((address_space(1)))
; template <int PASS>
; __device__ __forceinline__ void lru_unit(const LruPtrs& args, LAS unsigned char* lds, int chunk, int bl, int g, int ck) {
;     ...
;     if (PASS == 1) {
;         if (w == 0) { float A = 1.f, H = 0.f;
; #pragma unroll
;             for (int ww = 0; ww < 8; ++ww) { const float a = WAG[(ww * 64 + lane) * 2], h = WAG[(ww * 64 + lane) * 2 + 1]; H = a * H + h; A = A * a; }
;             GAS float* dst = AGG + ((size_t)(bl * 32 + ck) * D + g * 64 + lane) * 2; dst[0] = A; dst[1] = H; }
;         __syncthreads();
; __global__ void __launch_bounds__(NWAVES * 64, 2) hybrid_fwd(Args args) {
;     ...
;             pg8::Gemm g{LDZ, D, 256}; SchedMemS S{G, c, chunk, Z, MK}; pg8::EpiSoftmax E{(PG8_LAS float*)(lds + XS_OFF)};
;             pg8::gemm_phase<pg8::EpiSoftmax, SchedMemS>(lds + RING_OFF, g, S, E);
.LBB0_447:
	s_or_b64 exec, exec, s[4:5]
	s_cmp_gt_u32 s18, 63
	s_waitcnt lgkmcnt(0)
	s_barrier
	s_cbranch_scc1 .LBB0_403
	v_lshlrev_b32_e32 v0, 3, v86
	v_add_u32_e32 v0, 0, v0
	ds_read2st64_b64 v[2:5], v0 offset1:1
	ds_read2st64_b64 v[6:9], v0 offset0:2 offset1:3
	ds_read2st64_b64 v[10:13], v0 offset0:4 offset1:5
	ds_read2st64_b64 v[14:17], v0 offset0:6 offset1:7
	s_lshl_b32 s2, s46, 15
	s_waitcnt lgkmcnt(3)
	v_fma_f32 v0, 0, v2, v3
	v_fmac_f32_e32 v5, v0, v4
	s_waitcnt lgkmcnt(2)
	v_fma_f32 v0, v5, v6, v7
	v_fma_f32 v0, v0, v8, v9
	v_mul_f32_e32 v2, v2, v4
	s_waitcnt lgkmcnt(1)
	v_fma_f32 v3, v0, v10, v11
	v_mov_b32_e32 v7, v12
	v_pk_mul_f32 v[18:19], v[2:3], v[6:7]
	v_mov_b32_e32 v9, v13
	s_lshl_b32 s4, s45, 10
	v_pk_mul_f32 v[8:9], v[18:19], v[8:9]
	v_pk_fma_f32 v[2:3], v[2:3], v[6:7], v[12:13]
	s_or_b32 s2, s2, s4
	v_mov_b32_e32 v9, v3
	s_waitcnt lgkmcnt(0)
	v_mov_b32_e32 v11, v14
	s_or_b32 s2, s2, s44
	v_pk_mul_f32 v[6:7], v[8:9], v[10:11]
	v_or_b32_e32 v0, s2, v86
	v_mov_b32_e32 v3, v14
	v_pk_mul_f32 v[6:7], v[6:7], v[12:13]
	v_pk_fma_f32 v[8:9], v[8:9], v[10:11], v[14:15]
	v_lshlrev_b32_e32 v0, 1, v0
	v_mov_b32_e32 v8, v6
	v_pk_mov_b32 v[2:3], v[2:3], v[16:17] op_sel:[1,0]
	v_lshl_add_u64 v[4:5], v[0:1], 2, s[42:43]
	v_pk_mul_f32 v[6:7], v[6:7], v[2:3]
	v_pk_fma_f32 v[2:3], v[8:9], v[2:3], v[16:17]
	v_pk_mul_f32 v[6:7], v[6:7], v[16:17]
	v_add_co_u32_e32 v2, vcc, 0x3600000, v4
	v_mov_b32_e32 v7, v3
	s_nop 0
	v_addc_co_u32_e32 v3, vcc, 0, v5, vcc
	global_store_dwordx2 v[2:3], v[6:7], off
	s_cmp_eq_u32 s99, 0
	s_cbranch_scc1 .Lqwc
	s_and_saveexec_b64 s[100:101], s[10:11]
	v_mov_b32_e32 v253, s86
	ds_write_b32 v253, v252
	s_or_b64 exec, exec, s[100:101]
	s_waitcnt lgkmcnt(0)
.Lqwc:
	s_branch .LBB0_403
.LBB0_449:
	s_waitcnt vmcnt(0)
	s_add_u32 s46, s36, 0x2a00000
	s_addc_u32 s47, s37, 0
	v_mov_b32_e32 v10, v236
	s_cmpk_lt_i32 s96, 0x100
	s_mov_b32 s17, s91
	s_cselect_b64 s[6:7], -1, 0
	s_cmpk_gt_i32 s96, 0xff
	v_readfirstlane_b32 s2, v10
	s_cbranch_scc1 .LBB0_451
	s_ashr_i32 s4, s96, 7
	s_ashr_i32 s5, s4, 31
	s_lshl_b64 s[8:9], s[4:5], 24
	s_add_u32 s5, s93, s8
	s_addc_u32 s8, s16, s9
	s_lshl_b32 s9, s96, 19
	s_and_b32 s9, s9, 0xf80000
	s_add_u32 s5, s5, s9
	s_addc_u32 s8, s8, 0
	s_lshl_b32 s9, s96, 4
	s_and_b32 s9, s9, 0x600
	s_add_u32 s5, s5, s9
	s_addc_u32 s8, s8, 0
	s_add_u32 s42, s5, 0xc000000
	s_addc_u32 s43, s8, 0
	s_lshl_b32 s5, s95, 9
	s_lshl_b32 s4, s4, 8
	s_add_i32 s4, s4, s5
	s_ashr_i32 s5, s4, 31
	s_lshl_b64 s[4:5], s[4:5], 11
	s_add_u32 s4, s46, s4
	s_addc_u32 s5, s47, s5
	s_add_u32 s90, s4, s9
	s_addc_u32 s91, s5, 0

; __device__ __forceinline__ int crow(int r,int hi){return (r&3)+8*(r>>2)+4*hi;}
; template<int THRL> __device__ __forceinline__ void attn_unit(int b,int h,int qb,const bf16*Q,const bf16*__restrict__ K,const bf16*__restrict__ V,bf16*O,const bf16*GF,const float*CBh,const unsigned*KN,const unsigned*QN,char*shm){
;     ...
;   if(hi==0)wsf[32+r32]=l_reg;asm volatile("s_waitcnt lgkmcnt(0)":::"memory");
;   float rli[16];
;   #pragma unroll
;   for(int r=0;r<16;++r)rli[r]=__builtin_amdgcn_rcpf(wsf[32+crow(r,hi)]);
;   bf16*Ow=O+(rowbase+q0+wid*QBLK)*DM+h*D;
;   const bf16*Gw=GF+(rowbase+q0+wid*QBLK)*DM+h*D;
;   { bf16*stg=(bf16*)(shm+LDS_OST)+wid*2048;
;     #pragma unroll
;     for(int r=0;r<16;++r){const int orow=crow(r,hi);
;       #pragma unroll
;       for(int d0=0;d0<2;++d0)stg[orow*64+d0*32+r32]=__float2bfloat16(o[d0][r]*rli[r]);}
;     asm volatile("s_waitcnt lgkmcnt(0)":::"memory");
.LBB0_534:
	s_or_b64 exec, exec, s[6:7]
	s_waitcnt lgkmcnt(0)
	ds_read_b128 v[34:37], v216 offset:49280
	ds_read_b128 v[38:41], v216 offset:49312
	s_lshl_b64 s[6:7], s[42:43], 1
	s_add_u32 s2, s62, s6
	s_addc_u32 s7, s63, s7
	s_waitcnt lgkmcnt(1)
	v_rcp_f32_e32 v0, v34
	v_rcp_f32_e32 v42, v35
	s_lshl_b32 s6, s67, 12
	s_add_i32 s8, s6, 0
	v_lshl_add_u32 v49, v190, 1, s8
	v_mul_f32_e32 v18, v18, v0
	v_mul_f32_e32 v0, v2, v0
	v_rcp_f32_e32 v43, v36
	v_lshl_add_u32 v50, v191, 9, v49
	v_cvt_pk_bf16_f32 v0, v0, s0
	v_rcp_f32_e32 v44, v37
	s_waitcnt lgkmcnt(0)
	v_rcp_f32_e32 v45, v38
	ds_read_b128 v[34:37], v216 offset:49344
	v_rcp_f32_e32 v46, v39
	v_rcp_f32_e32 v47, v40
	v_rcp_f32_e32 v48, v41
	ds_read_b128 v[38:41], v216 offset:49376
	ds_write_b16 v50, v0 offset:51264
	v_mul_f32_e32 v0, v19, v42
	v_cvt_pk_bf16_f32 v0, v0, s0
	ds_write_b16 v50, v0 offset:51328
	v_mul_f32_e32 v0, v3, v42
	v_cvt_pk_bf16_f32 v0, v0, s0
	v_mul_f32_e32 v2, v20, v43
	ds_write_b16 v50, v0 offset:51392
	v_lshl_add_u32 v0, v213, 7, v49
	v_cvt_pk_bf16_f32 v2, v2, s0
	ds_write_b16 v0, v2 offset:51200
	v_mul_f32_e32 v2, v4, v43
	v_cvt_pk_bf16_f32 v2, v2, s0
	ds_write_b16 v0, v2 offset:51264
	v_mul_f32_e32 v2, v21, v44
	v_lshl_add_u32 v0, v212, 7, v49
	v_cvt_pk_bf16_f32 v2, v2, s0
	ds_write_b16 v0, v2 offset:51200
	v_mul_f32_e32 v2, v5, v44
	v_cvt_pk_bf16_f32 v2, v2, s0
	ds_write_b16 v0, v2 offset:51264
	v_mul_f32_e32 v2, v22, v45
	v_lshl_add_u32 v0, v211, 7, v49
	v_cvt_pk_bf16_f32 v2, v2, s0
	ds_write_b16 v0, v2 offset:51200
	v_mul_f32_e32 v2, v6, v45
	v_cvt_pk_bf16_f32 v2, v2, s0
	ds_write_b16 v0, v2 offset:51264
	v_mul_f32_e32 v2, v23, v46
	v_lshl_add_u32 v0, v210, 7, v49
	v_cvt_pk_bf16_f32 v2, v2, s0
	ds_write_b16 v0, v2 offset:51200
	v_mul_f32_e32 v2, v7, v46
	v_cvt_pk_bf16_f32 v2, v2, s0
	ds_write_b16 v0, v2 offset:51264
	v_mul_f32_e32 v2, v24, v47
	v_lshl_add_u32 v0, v209, 7, v49
	v_cvt_pk_bf16_f32 v2, v2, s0
	ds_write_b16 v0, v2 offset:51200
	v_mul_f32_e32 v2, v8, v47
	v_cvt_pk_bf16_f32 v2, v2, s0
	s_waitcnt lgkmcnt(13)
	v_rcp_f32_e32 v34, v34
	ds_write_b16 v0, v2 offset:51264
	v_mul_f32_e32 v2, v25, v48
	v_lshl_add_u32 v0, v208, 7, v49
	v_cvt_pk_bf16_f32 v2, v2, s0
	ds_write_b16 v0, v2 offset:51200
	v_mul_f32_e32 v2, v9, v48
	v_cvt_pk_bf16_f32 v2, v2, s0
	v_rcp_f32_e32 v35, v35
	ds_write_b16 v0, v2 offset:51264
	v_mul_f32_e32 v2, v26, v34
	v_lshl_add_u32 v0, v207, 7, v49
	v_cvt_pk_bf16_f32 v2, v2, s0
	ds_write_b16 v0, v2 offset:51200
	v_mul_f32_e32 v2, v10, v34
	v_cvt_pk_bf16_f32 v2, v2, s0
	v_rcp_f32_e32 v36, v36
	ds_write_b16 v0, v2 offset:51264
	v_mul_f32_e32 v2, v27, v35
	v_lshl_add_u32 v0, v206, 7, v49
	v_cvt_pk_bf16_f32 v2, v2, s0
	ds_write_b16 v0, v2 offset:51200
	v_mul_f32_e32 v2, v11, v35
	v_cvt_pk_bf16_f32 v2, v2, s0
	v_rcp_f32_e32 v37, v37
	ds_write_b16 v0, v2 offset:51264
	v_mul_f32_e32 v2, v28, v36
	v_lshl_add_u32 v0, v205, 7, v49
	v_cvt_pk_bf16_f32 v2, v2, s0
	ds_write_b16 v0, v2 offset:51200
	v_mul_f32_e32 v2, v12, v36
	v_cvt_pk_bf16_f32 v2, v2, s0
	s_waitcnt lgkmcnt(14)
	v_rcp_f32_e32 v38, v38
	ds_write_b16 v0, v2 offset:51264
	v_mul_f32_e32 v2, v29, v37
	v_lshl_add_u32 v0, v204, 7, v49
	v_cvt_pk_bf16_f32 v2, v2, s0
	ds_write_b16 v0, v2 offset:51200
	v_mul_f32_e32 v2, v13, v37
	v_cvt_pk_bf16_f32 v2, v2, s0
	v_rcp_f32_e32 v39, v39
	ds_write_b16 v0, v2 offset:51264
	v_mul_f32_e32 v2, v30, v38
	v_lshl_add_u32 v0, v203, 7, v49
	v_cvt_pk_bf16_f32 v2, v2, s0
	ds_write_b16 v0, v2 offset:51200
	v_mul_f32_e32 v2, v14, v38
	v_cvt_pk_bf16_f32 v2, v2, s0
	v_rcp_f32_e32 v40, v40
	ds_write_b16 v0, v2 offset:51264
	v_mul_f32_e32 v2, v31, v39
	v_lshl_add_u32 v0, v202, 7, v49
	v_cvt_pk_bf16_f32 v2, v2, s0
	ds_write_b16 v0, v2 offset:51200
	v_mul_f32_e32 v2, v15, v39
	v_cvt_pk_bf16_f32 v2, v2, s0
	v_rcp_f32_e32 v41, v41
	ds_write_b16 v0, v2 offset:51264
	v_mul_f32_e32 v2, v32, v40
	v_lshl_add_u32 v0, v193, 7, v49
	v_cvt_pk_bf16_f32 v2, v2, s0
	ds_write_b16 v0, v2 offset:51200
	v_mul_f32_e32 v2, v16, v40
	v_cvt_pk_bf16_f32 v2, v2, s0
	ds_write_b16 v0, v2 offset:51264
	v_mul_f32_e32 v2, v33, v41
	v_lshl_add_u32 v0, v187, 7, v49
	v_cvt_pk_bf16_f32 v2, v2, s0
	ds_write_b16 v0, v2 offset:51200
	v_mul_f32_e32 v2, v17, v41
	v_cvt_pk_bf16_f32 v2, v2, s0
	ds_write_b16 v0, v2 offset:51264
	s_add_u32 s6, s2, s66
	v_lshlrev_b32_e32 v0, 1, v189
	v_cvt_pk_bf16_f32 v18, v18, s0
	s_addc_u32 s7, s7, 0
	v_and_b32_e32 v0, 0x70, v0
	ds_write_b16 v50, v18 offset:51200
	v_lshl_add_u64 v[2:3], s[6:7], 0, v[0:1]
	v_and_b32_e32 v4, 0x3800, v186
	v_mov_b32_e32 v5, v1
	s_waitcnt lgkmcnt(0)
; template<int THRL> __device__ __forceinline__ void attn_unit(int b,int h,int qb,const bf16*Q,const bf16*__restrict__ K,const bf16*__restrict__ V,bf16*O,const bf16*GF,const float*CBh,const unsigned*KN,const unsigned*QN,char*shm){
;     ...
;     asm volatile("s_waitcnt lgkmcnt(0)":::"memory");
;     u32x4 gg[4];
;     #pragma unroll
;     for(int i=0;i<4;++i){const int row=i*8+(lane>>3),ch=lane&7; gg[i]=*(const u32x4*)(Gw+(long)row*DM+ch*8);}
;     #pragma unroll
;     for(int i=0;i<4;++i){const int row=i*8+(lane>>3),ch=lane&7; const u32x4 v=*(const u32x4*)(stg+row*64+ch*8);
;       *(u32x4*)(Ow+(long)row*DM+ch*8)=mul_bf16x8(v,gg[i]);} }
;   asm volatile("s_waitcnt vmcnt(0) lgkmcnt(0)\n\ts_barrier":::"memory");
	v_lshl_add_u64 v[2:3], v[2:3], 0, v[4:5]
	global_load_dwordx4 v[8:11], v[2:3], off
	v_add_co_u32_e32 v4, vcc, s31, v2
	s_mov_b32 s2, 0xc000
	s_nop 0
	v_addc_co_u32_e32 v5, vcc, 0, v3, vcc
	global_load_dwordx4 v[12:15], v[4:5], off
	v_add_co_u32_e32 v4, vcc, s79, v2
	v_lshrrev_b32_e32 v32, 3, v188
	s_nop 0
	v_addc_co_u32_e32 v5, vcc, 0, v3, vcc
	global_load_dwordx4 v[16:19], v[4:5], off
	v_add_co_u32_e32 v2, vcc, s2, v2
	v_add_u32_e32 v33, s8, v0
	s_nop 0
	v_addc_co_u32_e32 v3, vcc, 0, v3, vcc
	global_load_dwordx4 v[2:5], v[2:3], off
	v_lshl_add_u32 v6, v32, 7, v33
	ds_read_b128 v[20:23], v6 offset:51200
	v_or_b32_e32 v34, 8, v32
	v_lshl_add_u64 v[6:7], s[14:15], 0, v[0:1]
	v_lshl_add_u32 v0, v34, 7, v33
	ds_read_b128 v[24:27], v0 offset:51200
	s_waitcnt lgkmcnt(1)
	v_lshlrev_b32_e32 v28, 16, v20
	v_and_b32_e32 v29, 0xffff0000, v20
	v_lshlrev_b32_e32 v20, 16, v21
	v_and_b32_e32 v21, 0xffff0000, v21
	v_lshlrev_b32_e32 v0, 11, v32
	s_waitcnt vmcnt(3)
	v_lshlrev_b32_e32 v30, 16, v8
	v_and_b32_e32 v31, 0xffff0000, v8
	v_pk_mul_f32 v[28:29], v[30:31], v[28:29]
	s_nop 0
	v_cvt_pk_bf16_f32 v8, v28, v29
	v_lshlrev_b32_e32 v28, 16, v9
	v_and_b32_e32 v29, 0xffff0000, v9
	v_pk_mul_f32 v[20:21], v[28:29], v[20:21]
	v_lshlrev_b32_e32 v28, 16, v10
	v_cvt_pk_bf16_f32 v9, v20, v21
	v_lshlrev_b32_e32 v20, 16, v22
	v_and_b32_e32 v21, 0xffff0000, v22
	v_and_b32_e32 v29, 0xffff0000, v10
	v_pk_mul_f32 v[20:21], v[28:29], v[20:21]
	v_lshlrev_b32_e32 v22, 16, v11
	v_cvt_pk_bf16_f32 v10, v20, v21
	v_lshlrev_b32_e32 v20, 16, v23
	v_and_b32_e32 v21, 0xffff0000, v23
	v_and_b32_e32 v23, 0xffff0000, v11
	v_pk_mul_f32 v[20:21], v[22:23], v[20:21]
	s_waitcnt vmcnt(1)
	v_lshlrev_b32_e32 v22, 16, v16
	v_cvt_pk_bf16_f32 v11, v20, v21
	v_lshl_add_u64 v[20:21], v[6:7], 0, v[0:1]
	global_store_dwordx4 v[20:21], v[8:11], off
	v_lshlrev_b32_e32 v0, 11, v34
	v_lshl_add_u64 v[20:21], v[6:7], 0, v[0:1]
	s_waitcnt lgkmcnt(0)
	v_lshlrev_b32_e32 v8, 16, v24
	v_and_b32_e32 v9, 0xffff0000, v24
	v_lshlrev_b32_e32 v10, 16, v12
	v_and_b32_e32 v11, 0xffff0000, v12
	v_pk_mul_f32 v[8:9], v[10:11], v[8:9]
	v_lshlrev_b32_e32 v10, 16, v25
	v_and_b32_e32 v11, 0xffff0000, v25
	v_lshlrev_b32_e32 v12, 16, v13
	v_and_b32_e32 v13, 0xffff0000, v13
	v_pk_mul_f32 v[10:11], v[12:13], v[10:11]
	v_cvt_pk_bf16_f32 v8, v8, v9
	v_cvt_pk_bf16_f32 v9, v10, v11
	v_lshlrev_b32_e32 v10, 16, v26
	v_and_b32_e32 v11, 0xffff0000, v26
	v_lshlrev_b32_e32 v12, 16, v14
	v_and_b32_e32 v13, 0xffff0000, v14
	v_pk_mul_f32 v[10:11], v[12:13], v[10:11]
	v_lshlrev_b32_e32 v12, 16, v27
	v_and_b32_e32 v13, 0xffff0000, v27
	v_lshlrev_b32_e32 v14, 16, v15
	v_and_b32_e32 v15, 0xffff0000, v15
	v_pk_mul_f32 v[12:13], v[14:15], v[12:13]
	v_or_b32_e32 v0, 16, v32
	v_cvt_pk_bf16_f32 v10, v10, v11
	v_cvt_pk_bf16_f32 v11, v12, v13
	v_lshl_add_u32 v12, v0, 7, v33
	ds_read_b128 v[12:15], v12 offset:51200
	v_or_b32_e32 v24, 24, v32
	global_store_dwordx4 v[20:21], v[8:11], off
	v_and_b32_e32 v23, 0xffff0000, v16
	v_lshlrev_b32_e32 v16, 16, v17
	v_lshl_add_u32 v8, v24, 7, v33
	ds_read_b128 v[8:11], v8 offset:51200
	s_waitcnt lgkmcnt(1)
	v_lshlrev_b32_e32 v20, 16, v12
	v_and_b32_e32 v21, 0xffff0000, v12
	v_pk_mul_f32 v[20:21], v[22:23], v[20:21]
	v_and_b32_e32 v17, 0xffff0000, v17
	v_cvt_pk_bf16_f32 v12, v20, v21
	v_lshlrev_b32_e32 v20, 16, v13
	v_and_b32_e32 v21, 0xffff0000, v13
	v_pk_mul_f32 v[16:17], v[16:17], v[20:21]
	v_lshlrev_b32_e32 v20, 16, v18
	v_cvt_pk_bf16_f32 v13, v16, v17
	v_lshlrev_b32_e32 v16, 16, v14
	v_and_b32_e32 v17, 0xffff0000, v14
	v_and_b32_e32 v21, 0xffff0000, v18
	v_pk_mul_f32 v[16:17], v[20:21], v[16:17]
	v_lshlrev_b32_e32 v18, 16, v19
	v_cvt_pk_bf16_f32 v14, v16, v17
	v_lshlrev_b32_e32 v16, 16, v15
	v_and_b32_e32 v17, 0xffff0000, v15
	v_and_b32_e32 v19, 0xffff0000, v19
	v_pk_mul_f32 v[16:17], v[18:19], v[16:17]
	v_lshlrev_b32_e32 v0, 11, v0
	v_cvt_pk_bf16_f32 v15, v16, v17
	v_lshl_add_u64 v[16:17], v[6:7], 0, v[0:1]
	global_store_dwordx4 v[16:17], v[12:15], off
	v_lshlrev_b32_e32 v0, 11, v24
	v_lshl_add_u64 v[6:7], v[6:7], 0, v[0:1]
	s_waitcnt lgkmcnt(0)
	v_lshlrev_b32_e32 v12, 16, v8
	v_and_b32_e32 v13, 0xffff0000, v8
	s_waitcnt vmcnt(3)
	v_lshlrev_b32_e32 v14, 16, v2
	v_and_b32_e32 v15, 0xffff0000, v2
	v_pk_mul_f32 v[12:13], v[14:15], v[12:13]
	v_lshlrev_b32_e32 v8, 16, v9
	v_cvt_pk_bf16_f32 v2, v12, v13
	v_and_b32_e32 v9, 0xffff0000, v9
	v_lshlrev_b32_e32 v12, 16, v3
	v_and_b32_e32 v13, 0xffff0000, v3
	v_pk_mul_f32 v[8:9], v[12:13], v[8:9]
	v_lshlrev_b32_e32 v12, 16, v4
	v_cvt_pk_bf16_f32 v3, v8, v9
	v_lshlrev_b32_e32 v8, 16, v10
	v_and_b32_e32 v9, 0xffff0000, v10
	v_and_b32_e32 v13, 0xffff0000, v4
	v_pk_mul_f32 v[8:9], v[12:13], v[8:9]
	v_lshlrev_b32_e32 v10, 16, v5
	v_cvt_pk_bf16_f32 v4, v8, v9
	v_lshlrev_b32_e32 v8, 16, v11
	v_and_b32_e32 v9, 0xffff0000, v11
	v_and_b32_e32 v11, 0xffff0000, v5
	v_pk_mul_f32 v[8:9], v[10:11], v[8:9]
	s_nop 0
	v_cvt_pk_bf16_f32 v5, v8, v9
	global_store_dwordx4 v[6:7], v[2:5], off
	s_cmp_eq_u32 s99, 0
	s_cbranch_scc1 .Lqwa
	s_and_saveexec_b64 s[100:101], s[10:11]
	v_mov_b32_e32 v253, s86
	ds_write_b32 v253, v252
	s_or_b64 exec, exec, s[100:101]
	s_waitcnt lgkmcnt(0)
.Lqwa:
	s_waitcnt vmcnt(0) lgkmcnt(0)
	s_barrier

; __global__ void __launch_bounds__(NWAVES * 64, 2) hybrid_fwd(Args args) {
;     ...
;                 for (;;) {
;                     if (threadIdx.x == 0) *slot = __hip_atomic_fetch_add(qc, 1u, __ATOMIC_RELAXED, __HIP_MEMORY_SCOPE_AGENT);
;                     __syncthreads();
;                     const int L = __builtin_amdgcn_readfirstlane((int)*slot);
.LBB0_537:
	s_cmp_eq_u32 s99, 0
	s_cbranch_scc1 .Lq3_slow
	v_mov_b32_e32 v0, s86
	ds_read_b32 v0, v0
	s_mov_b64 s[6:7], -1
	s_waitcnt lgkmcnt(0)
	s_branch .Lq3_join

; __global__ void __launch_bounds__(NWAVES * 64, 2) hybrid_fwd(Args args) {
;     ...
;                     if (threadIdx.x == 0) *slot = __hip_atomic_fetch_add(qc, 1u, __ATOMIC_RELAXED, __HIP_MEMORY_SCOPE_AGENT);
;                     __syncthreads();
;                     const int L = __builtin_amdgcn_readfirstlane((int)*slot);
;                     __syncthreads();
;                     if (L >= 2 * CHB * 16 * 32) break;
;                     if (L < CHB * 16 * 32) { const int qb = 31 - (L >> 5), bh = L & 31;
.Lq3_join:
	v_readfirstlane_b32 s2, v0
	s_cmpk_gt_i32 s2, 0x7ff
	s_cbranch_scc1 .LBB0_536
	s_mov_b32 s99, 0
	s_cmpk_lt_i32 s2, 0x6c0
	s_cbranch_scc0 .Lq3_nopf
	s_mov_b32 s99, 1
	s_and_saveexec_b64 s[8:9], s[10:11]
	s_cbranch_execz .Lq3_nopx
	v_mov_b32_e32 v252, v230
	global_atomic_add v252, v1, v252, s[38:39] offset:256 sc0

; __device__ __forceinline__ unsigned cvt_pk_bf16(float lo, float hi) { unsigned r; asm volatile("v_cvt_pk_bf16_f32 %0, %1, %2" : "=v"(r) : "v"(lo), "v"(hi)); return r; }
; #define LAS __attribute__((address_space(3)))
; template <int PASS>
; __device__ __forceinline__ void lru_unit(const LruPtrs& args, LAS unsigned char* lds, int chunk, int bl, int g, int ck) {
;     ...
;         LAS bf16* GT = (LAS bf16*)(lds + RING_OFF + 32768 + w * 4864);
; #pragma unroll
;         for (int i = 0; i < 4; ++i) { const int idx = lane + 64 * i, r = idx >> 3, ch = idx & 7;
;             *(LAS v2u*)(GT + r * 68 + ch * 8) = (v2u){gtile[i].x, gtile[i].y}; *(LAS v2u*)(GT + r * 68 + ch * 8 + 4) = (v2u){gtile[i].z, gtile[i].w}; }
;         asm volatile("s_waitcnt lgkmcnt(0)" ::: "memory");
; #pragma unroll
;         for (int q = 0; q < 8; ++q) { const f32x4 cr = *(const LAS f32x4*)(CARW + w * 64 + 8 * q + 4 * hi);
;             LAS v2u* gl = (LAS v2u*)(GT + n * 68 + 8 * q + 4 * hi);
;             const v2u gw = *gl;
;             const float h0 = (uv[q][0] + av[q][0] * cr[0]) * pg8::bf_lo(gw.x), h1 = (uv[q][1] + av[q][1] * cr[1]) * pg8::bf_hi(gw.x);
;             const float h2 = (uv[q][2] + av[q][2] * cr[2]) * pg8::bf_lo(gw.y), h3 = (uv[q][3] + av[q][3] * cr[3]) * pg8::bf_hi(gw.y);
;             v2u o; o.x = pg8::cvt_pk_bf16(h0, h1); o.y = pg8::cvt_pk_bf16(h2, h3); *gl = o; }
.LBB0_556:
	s_mulk_i32 s14, 0x1300
	v_and_b32_e32 v59, 0xffff0000, v5
	v_lshlrev_b32_e32 v60, 16, v5
	s_add_i32 s6, s14, 0
	v_mul_u32_u24_e32 v5, 0x88, v69
	v_add3_u32 v0, s6, v0, v5
	v_lshrrev_b32_e32 v58, 3, v68
	v_and_b32_e32 v61, 0xffff0000, v4
	v_lshlrev_b32_e32 v62, 16, v4
	v_and_b32_e32 v4, 31, v68
	v_add_u32_e32 v68, 0x8000, v0
	s_waitcnt lgkmcnt(0)
	s_barrier
	ds_write2_b64 v68, v[30:31], v[32:33] offset1:1
	v_add_u32_e32 v32, 0x8440, v0
	v_add_u32_e32 v33, 0x8880, v0
	v_add_u32_e32 v0, 0x8cc0, v0
	s_lshl_b32 s7, s15, 2
	v_and_b32_e32 v58, 4, v58
	ds_write2_b64 v32, v[34:35], v[36:37] offset1:1
	ds_write2_b64 v33, v[42:43], v[44:45] offset1:1
	ds_write2_b64 v0, v[46:47], v[48:49] offset1:1
	s_add_i32 s7, s7, 0
	s_waitcnt lgkmcnt(0)
	v_lshl_add_u32 v34, v58, 2, s7
	v_mul_u32_u24_e32 v4, 0x88, v4
	v_lshlrev_b32_e32 v5, 1, v58
	v_and_b32_e32 v64, 0xffff0000, v9
	v_lshlrev_b32_e32 v65, 16, v9
	v_and_b32_e32 v66, 0xffff0000, v8
	v_lshlrev_b32_e32 v67, 16, v8
	v_and_b32_e32 v8, 0xffff0000, v13
	v_lshlrev_b32_e32 v9, 16, v13
	v_and_b32_e32 v71, 0xffff0000, v12
	v_lshlrev_b32_e32 v72, 16, v12
	v_and_b32_e32 v12, 0xffff0000, v17
	v_lshlrev_b32_e32 v13, 16, v17
	v_and_b32_e32 v74, 0xffff0000, v16
	v_lshlrev_b32_e32 v75, 16, v16
	v_and_b32_e32 v16, 0xffff0000, v21
	v_lshlrev_b32_e32 v17, 16, v21
	v_and_b32_e32 v77, 0xffff0000, v20
	v_lshlrev_b32_e32 v78, 16, v20
	v_and_b32_e32 v20, 0xffff0000, v25
	v_lshlrev_b32_e32 v21, 16, v25
	v_and_b32_e32 v80, 0xffff0000, v24
	v_lshlrev_b32_e32 v81, 16, v24
	v_and_b32_e32 v24, 0xffff0000, v29
	v_lshlrev_b32_e32 v25, 16, v29
	v_and_b32_e32 v83, 0xffff0000, v28
	v_lshlrev_b32_e32 v84, 16, v28
	v_add3_u32 v35, s6, v4, v5
	ds_read_b128 v[28:31], v34 offset:8192
	ds_read_b64 v[4:5], v35 offset:32768
	v_and_b32_e32 v86, 0xffff0000, v41
	v_lshlrev_b32_e32 v41, 16, v41
	v_and_b32_e32 v88, 0xffff0000, v39
	v_lshlrev_b32_e32 v36, 16, v39
	v_and_b32_e32 v37, 0xffff0000, v38
	v_lshlrev_b32_e32 v38, 16, v38
	v_and_b32_e32 v87, 0xffff0000, v40
	v_lshlrev_b32_e32 v40, 16, v40
	s_waitcnt lgkmcnt(1)
	v_fmac_f32_e32 v37, v28, v38
	s_waitcnt lgkmcnt(0)
	v_lshlrev_b32_e32 v28, 16, v4
	v_fmac_f32_e32 v88, v29, v36
	v_and_b32_e32 v4, 0xffff0000, v4
	v_lshlrev_b32_e32 v29, 16, v5
	v_fmac_f32_e32 v86, v31, v41
	v_and_b32_e32 v5, 0xffff0000, v5
	v_mul_f32_e32 v4, v88, v4
	v_fmac_f32_e32 v87, v30, v40
	v_mul_f32_e32 v5, v86, v5
	v_mul_f32_e32 v28, v37, v28
	v_mul_f32_e32 v29, v87, v29
	v_cvt_pk_bf16_f32 v4, v28, v4
	v_cvt_pk_bf16_f32 v5, v29, v5
	ds_write_b64 v35, v[4:5] offset:32768
	ds_read_b128 v[28:31], v34 offset:8224
	ds_read_b64 v[4:5], v35 offset:32784
	v_and_b32_e32 v85, 0xffff0000, v27
	v_lshlrev_b32_e32 v27, 16, v27
	v_and_b32_e32 v36, 0xffff0000, v26
	v_lshlrev_b32_e32 v26, 16, v26
	s_waitcnt lgkmcnt(1)
	v_fmac_f32_e32 v36, v28, v26
	s_waitcnt lgkmcnt(0)
	v_lshlrev_b32_e32 v26, 16, v4
	v_fmac_f32_e32 v85, v29, v27
	v_and_b32_e32 v4, 0xffff0000, v4
	v_lshlrev_b32_e32 v27, 16, v5
	v_fmac_f32_e32 v24, v31, v25
	v_and_b32_e32 v5, 0xffff0000, v5
	v_mul_f32_e32 v4, v85, v4
	v_fmac_f32_e32 v83, v30, v84
	v_mul_f32_e32 v5, v24, v5
	v_mul_f32_e32 v26, v36, v26
	v_mul_f32_e32 v27, v83, v27
	v_cvt_pk_bf16_f32 v4, v26, v4
	v_cvt_pk_bf16_f32 v5, v27, v5
	ds_write_b64 v35, v[4:5] offset:32784
	ds_read_b128 v[24:27], v34 offset:8256
	ds_read_b64 v[4:5], v35 offset:32800
	v_and_b32_e32 v82, 0xffff0000, v23
	v_lshlrev_b32_e32 v23, 16, v23
	v_and_b32_e32 v28, 0xffff0000, v22
	v_lshlrev_b32_e32 v22, 16, v22
	s_waitcnt lgkmcnt(1)
	v_fmac_f32_e32 v28, v24, v22
	s_waitcnt lgkmcnt(0)
	v_lshlrev_b32_e32 v22, 16, v4
	v_fmac_f32_e32 v82, v25, v23
	v_and_b32_e32 v4, 0xffff0000, v4
	v_lshlrev_b32_e32 v23, 16, v5
	v_fmac_f32_e32 v20, v27, v21
	v_and_b32_e32 v5, 0xffff0000, v5
	v_mul_f32_e32 v4, v82, v4
	v_fmac_f32_e32 v80, v26, v81
	v_mul_f32_e32 v5, v20, v5
	v_mul_f32_e32 v22, v28, v22
	v_mul_f32_e32 v23, v80, v23
	v_cvt_pk_bf16_f32 v4, v22, v4
	v_cvt_pk_bf16_f32 v5, v23, v5
	ds_write_b64 v35, v[4:5] offset:32800
	ds_read_b128 v[20:23], v34 offset:8288
	ds_read_b64 v[4:5], v35 offset:32816
	v_and_b32_e32 v79, 0xffff0000, v19
	v_lshlrev_b32_e32 v19, 16, v19
	v_and_b32_e32 v24, 0xffff0000, v18
	v_lshlrev_b32_e32 v18, 16, v18
	s_waitcnt lgkmcnt(1)
; __device__ __forceinline__ unsigned cvt_pk_bf16(float lo, float hi) { unsigned r; asm volatile("v_cvt_pk_bf16_f32 %0, %1, %2" : "=v"(r) : "v"(lo), "v"(hi)); return r; }
; #define GAS __attribute__((address_space(1)))
; #define LAS __attribute__((address_space(3)))
; template <int PASS>
; __device__ __forceinline__ void lru_unit(const LruPtrs& args, LAS unsigned char* lds, int chunk, int bl, int g, int ck) {
;     ...
; #pragma unroll
;         for (int q = 0; q < 8; ++q) { const f32x4 cr = *(const LAS f32x4*)(CARW + w * 64 + 8 * q + 4 * hi);
;             LAS v2u* gl = (LAS v2u*)(GT + n * 68 + 8 * q + 4 * hi);
;             const v2u gw = *gl;
;             const float h0 = (uv[q][0] + av[q][0] * cr[0]) * pg8::bf_lo(gw.x), h1 = (uv[q][1] + av[q][1] * cr[1]) * pg8::bf_hi(gw.x);
;             const float h2 = (uv[q][2] + av[q][2] * cr[2]) * pg8::bf_lo(gw.y), h3 = (uv[q][3] + av[q][3] * cr[3]) * pg8::bf_hi(gw.y);
;             v2u o; o.x = pg8::cvt_pk_bf16(h0, h1); o.y = pg8::cvt_pk_bf16(h2, h3); *gl = o; }
;         asm volatile("s_waitcnt lgkmcnt(0)" ::: "memory");
; #pragma unroll
;         for (int i = 0; i < 4; ++i) { const int idx = lane + 64 * i, r = idx >> 3, ch = idx & 7;
;             const v2u a = *(const LAS v2u*)(GT + r * 68 + ch * 8), b = *(const LAS v2u*)(GT + r * 68 + ch * 8 + 4);
;             *(GAS v4u*)(Z + ((size_t)bl * T + ck * 256 + w * 32 + r) * LDZ + ZC_GA + g * 64 + ch * 8) = (v4u){a.x, a.y, b.x, b.y}; }
;         __syncthreads();
	v_fmac_f32_e32 v24, v20, v18
	s_waitcnt lgkmcnt(0)
	v_lshlrev_b32_e32 v18, 16, v4
	v_fmac_f32_e32 v79, v21, v19
	v_and_b32_e32 v4, 0xffff0000, v4
	v_lshlrev_b32_e32 v19, 16, v5
	v_fmac_f32_e32 v16, v23, v17
	v_and_b32_e32 v5, 0xffff0000, v5
	v_mul_f32_e32 v4, v79, v4
	v_fmac_f32_e32 v77, v22, v78
	v_mul_f32_e32 v5, v16, v5
	v_mul_f32_e32 v18, v24, v18
	v_mul_f32_e32 v19, v77, v19
	v_cvt_pk_bf16_f32 v4, v18, v4
	v_cvt_pk_bf16_f32 v5, v19, v5
	ds_write_b64 v35, v[4:5] offset:32816
	ds_read_b128 v[16:19], v34 offset:8320
	ds_read_b64 v[4:5], v35 offset:32832
	v_and_b32_e32 v76, 0xffff0000, v15
	v_lshlrev_b32_e32 v15, 16, v15
	v_and_b32_e32 v20, 0xffff0000, v14
	v_lshlrev_b32_e32 v14, 16, v14
	s_waitcnt lgkmcnt(1)
	v_fmac_f32_e32 v20, v16, v14
	s_waitcnt lgkmcnt(0)
	v_lshlrev_b32_e32 v14, 16, v4
	v_fmac_f32_e32 v76, v17, v15
	v_and_b32_e32 v4, 0xffff0000, v4
	v_lshlrev_b32_e32 v15, 16, v5
	v_fmac_f32_e32 v12, v19, v13
	v_and_b32_e32 v5, 0xffff0000, v5
	v_mul_f32_e32 v4, v76, v4
	v_fmac_f32_e32 v74, v18, v75
	v_mul_f32_e32 v5, v12, v5
	v_mul_f32_e32 v14, v20, v14
	v_mul_f32_e32 v15, v74, v15
	v_cvt_pk_bf16_f32 v4, v14, v4
	v_cvt_pk_bf16_f32 v5, v15, v5
	ds_write_b64 v35, v[4:5] offset:32832
	ds_read_b128 v[12:15], v34 offset:8352
	ds_read_b64 v[4:5], v35 offset:32848
	v_and_b32_e32 v73, 0xffff0000, v11
	v_lshlrev_b32_e32 v11, 16, v11
	v_and_b32_e32 v16, 0xffff0000, v10
	v_lshlrev_b32_e32 v10, 16, v10
	s_waitcnt lgkmcnt(1)
	v_fmac_f32_e32 v16, v12, v10
	s_waitcnt lgkmcnt(0)
	v_lshlrev_b32_e32 v10, 16, v4
	v_fmac_f32_e32 v73, v13, v11
	v_and_b32_e32 v4, 0xffff0000, v4
	v_lshlrev_b32_e32 v11, 16, v5
	v_fmac_f32_e32 v8, v15, v9
	v_and_b32_e32 v5, 0xffff0000, v5
	v_mul_f32_e32 v4, v73, v4
	v_fmac_f32_e32 v71, v14, v72
	v_mul_f32_e32 v5, v8, v5
	v_mul_f32_e32 v10, v16, v10
	v_mul_f32_e32 v11, v71, v11
	v_cvt_pk_bf16_f32 v4, v10, v4
	v_cvt_pk_bf16_f32 v5, v11, v5
	ds_write_b64 v35, v[4:5] offset:32848
	ds_read_b128 v[8:11], v34 offset:8384
	ds_read_b64 v[4:5], v35 offset:32864
	v_and_b32_e32 v70, 0xffff0000, v7
	v_lshlrev_b32_e32 v7, 16, v7
	v_and_b32_e32 v12, 0xffff0000, v6
	v_lshlrev_b32_e32 v6, 16, v6
	s_waitcnt lgkmcnt(1)
	v_fmac_f32_e32 v12, v8, v6
	s_waitcnt lgkmcnt(0)
	v_lshlrev_b32_e32 v6, 16, v4
	v_fmac_f32_e32 v70, v9, v7
	v_and_b32_e32 v4, 0xffff0000, v4
	v_lshlrev_b32_e32 v7, 16, v5
	v_fmac_f32_e32 v64, v11, v65
	v_and_b32_e32 v5, 0xffff0000, v5
	v_mul_f32_e32 v4, v70, v4
	v_fmac_f32_e32 v66, v10, v67
	v_mul_f32_e32 v5, v64, v5
	v_mul_f32_e32 v6, v12, v6
	v_mul_f32_e32 v7, v66, v7
	v_cvt_pk_bf16_f32 v4, v6, v4
	v_cvt_pk_bf16_f32 v5, v7, v5
	ds_write_b64 v35, v[4:5] offset:32864
	ds_read_b128 v[4:7], v34 offset:8416
	ds_read_b64 v[8:9], v35 offset:32880
	v_and_b32_e32 v63, 0xffff0000, v3
	v_lshlrev_b32_e32 v3, 16, v3
	v_and_b32_e32 v10, 0xffff0000, v2
	v_lshlrev_b32_e32 v2, 16, v2
	s_waitcnt lgkmcnt(1)
	v_fmac_f32_e32 v10, v4, v2
	s_waitcnt lgkmcnt(0)
	v_lshlrev_b32_e32 v2, 16, v8
	v_fmac_f32_e32 v63, v5, v3
	v_and_b32_e32 v3, 0xffff0000, v8
	v_mul_f32_e32 v2, v10, v2
	v_mul_f32_e32 v3, v63, v3
	v_fmac_f32_e32 v61, v6, v62
	v_lshlrev_b32_e32 v4, 16, v9
	v_fmac_f32_e32 v59, v7, v60
	v_and_b32_e32 v5, 0xffff0000, v9
	v_mul_f32_e32 v4, v61, v4
	v_mul_f32_e32 v5, v59, v5
	v_cvt_pk_bf16_f32 v2, v2, v3
	v_cvt_pk_bf16_f32 v3, v4, v5
	ds_write_b64 v35, v[2:3] offset:32880
	s_waitcnt lgkmcnt(0)
	ds_read2_b64 v[2:5], v68 offset1:1
	ds_read2_b64 v[6:9], v32 offset1:1
	ds_read2_b64 v[10:13], v33 offset1:1
	ds_read2_b64 v[14:17], v0 offset1:1
	v_lshl_add_u64 v[52:53], v[52:53], 0, s[34:35]
	v_lshl_add_u64 v[54:55], v[54:55], 0, s[34:35]
	v_lshl_add_u64 v[56:57], v[56:57], 0, s[34:35]
	v_lshl_add_u64 v[18:19], v[50:51], 0, s[34:35]
	s_waitcnt lgkmcnt(3)
	global_store_dwordx4 v[52:53], v[2:5], off
	s_waitcnt lgkmcnt(2)
	global_store_dwordx4 v[54:55], v[6:9], off
	s_waitcnt lgkmcnt(1)
	global_store_dwordx4 v[56:57], v[10:13], off
	s_waitcnt lgkmcnt(0)
	global_store_dwordx4 v[18:19], v[14:17], off
	s_cmp_eq_u32 s99, 0
	s_cbranch_scc1 .Lqwb
	s_and_saveexec_b64 s[100:101], s[10:11]
	v_mov_b32_e32 v253, s86
	ds_write_b32 v253, v252
	s_or_b64 exec, exec, s[100:101]
	s_waitcnt lgkmcnt(0)
.Lqwb:
	s_barrier
	s_mov_b64 s[6:7], 0
